# FFN-up: the nearly empty 17th m-tile (34 stored rows of 256) runs a reduced k-loop (wm=1 waves skip the MFMAs, wm=0 waves only the 3 row blocks whose results are stored)
# speedup vs baseline: 1.0020x; 1.0020x over previous
; template <int MI, int NJ, bool SWAP, class AP, class BP>
; DI void gemm_main(f32x4 (&acc)[MI][NJ], const AP& ap, int a_kstep, const BP& bp, int b_kstep, int nk, bf16_t* smem) {
;     ...
;   for (int kt = 0; kt < nk; ++kt) {
;     const int buf = kt & 1;
;     sstore(buf ^ 1);
;     gload(kt + 2 < nk ? kt + 2 : nk - 1);
;     __builtin_amdgcn_sched_barrier(0);
;     const bf16_t* As = smem + buf * L::STAGE + (wm * 16 * MI + l15) * LDT + quad * 8;
;     const bf16_t* Bs = smem + buf * L::STAGE + L::A_ELEMS + (wn * 16 * NJ + l15) * LDT + quad * 8;
; #pragma unroll
;     for (int ks = 0; ks < 2; ++ks) {
;       if (MI * NJ >= 32 && ks == 1) asm volatile("" ::: "memory");
;       bf16x8 b[NJ];
; #pragma unroll
;       for (int j = 0; j < NJ; ++j) b[j] = *(const bf16x8*)(Bs + j * 16 * LDT + ks * 32);
.LBB0_1049:
	s_cmp_eq_u32 s29, 0xfde
	s_cbranch_scc1 .Lgm6r_main
	s_and_b32 s98, s30, 1
	s_mul_i32 s98, s98, 0x12000
	v_add3_u32 v181, s98, v170, v180
	v_add3_u32 v202, s98, v171, v180
	ds_read_b128 v[198:201], v181
	ds_read_b128 v[242:245], v181 offset:2304
	ds_read_b128 v[182:185], v202 offset:36864
	ds_read_b128 v[186:189], v202 offset:39168
	ds_read_b128 v[190:193], v202 offset:41472
	ds_read_b128 v[194:197], v202 offset:43776

; DI f32x4 mfma16(bf16x8 a, bf16x8 b, f32x4 c) { return __builtin_amdgcn_mfma_f32_16x16x32_bf16(a, b, c, 0, 0, 0); }
; template <int MI, int NJ, bool SWAP, class AP, class BP>
; DI void gemm_main(f32x4 (&acc)[MI][NJ], const AP& ap, int a_kstep, const BP& bp, int b_kstep, int nk, bf16_t* smem) {
;     ...
;   auto gload = [&](int kt) {
;     const bf16_t* ab = ap.base + (size_t)kt * a_kstep; const bf16_t* bb = bp.base + (size_t)kt * b_kstep;
; #pragma unroll
;     for (int i = 0; i < CA; ++i) ra[i] = *(const u32x4*)(ab + pa[i]);
; #pragma unroll
;     for (int i = 0; i < CB; ++i) rb[i] = *(const u32x4*)(bb + pb[i]);
;   };
;   auto sstore = [&](int buf) {
;     bf16_t* As = smem + buf * L::STAGE; bf16_t* Bs = As + L::A_ELEMS;
; #pragma unroll
;     for (int i = 0; i < CA; ++i) { const int c = tid + NTHR * i; *(u32x4*)(As + (c >> 3) * LDT + (c & 7) * 8) = oka[i] ? ra[i] : (u32x4){0u, 0u, 0u, 0u}; }
; #pragma unroll
;     for (int i = 0; i < CB; ++i) { const int c = tid + NTHR * i; *(u32x4*)(Bs + (c >> 3) * LDT + (c & 7) * 8) = rb[i]; }
;   };
;   gload(0); sstore(0); gload(nk > 1 ? 1 : 0); __syncthreads();
; #pragma unroll 1
;   for (int kt = 0; kt < nk; ++kt) {
;     const int buf = kt & 1;
;     sstore(buf ^ 1);
;     gload(kt + 2 < nk ? kt + 2 : nk - 1);
;     __builtin_amdgcn_sched_barrier(0);
;     const bf16_t* As = smem + buf * L::STAGE + (wm * 16 * MI + l15) * LDT + quad * 8;
;     const bf16_t* Bs = smem + buf * L::STAGE + L::A_ELEMS + (wn * 16 * NJ + l15) * LDT + quad * 8;
; #pragma unroll
;     for (int ks = 0; ks < 2; ++ks) {
;       if (MI * NJ >= 32 && ks == 1) asm volatile("" ::: "memory");
;       bf16x8 b[NJ];
; #pragma unroll
;       for (int j = 0; j < NJ; ++j) b[j] = *(const bf16x8*)(Bs + j * 16 * LDT + ks * 32);
; #pragma unroll
;       for (int i = 0; i < MI; ++i) {
;         const bf16x8 a = *(const bf16x8*)(As + i * 16 * LDT + ks * 32);
; #pragma unroll
;         for (int j = 0; j < NJ; ++j) acc[i][j] = SWAP ? mfma16(b[j], a, acc[i][j]) : mfma16(a, b[j], acc[i][j]);
;       }
.Lgm6_exit:
	v_mfma_f32_16x16x32_bf16 v[28:31], v[182:185], v[246:249], v[28:31]
	v_mfma_f32_16x16x32_bf16 v[12:15], v[182:185], v[250:253], v[12:15]
	v_mfma_f32_16x16x32_bf16 v[24:27], v[186:189], v[246:249], v[24:27]
	v_mfma_f32_16x16x32_bf16 v[8:11], v[186:189], v[250:253], v[8:11]
	v_mfma_f32_16x16x32_bf16 v[20:23], v[190:193], v[246:249], v[20:23]
	v_mfma_f32_16x16x32_bf16 v[4:7], v[190:193], v[250:253], v[4:7]
	v_mfma_f32_16x16x32_bf16 v[16:19], v[194:197], v[246:249], v[16:19]
	v_mfma_f32_16x16x32_bf16 v[0:3], v[194:197], v[250:253], v[0:3]
	s_nop 7
	s_branch .Lgm6_done
.Lgm6r_main:
	s_and_b32 s31, s30, 1
	s_xor_b32 s33, s31, 1
	s_mul_i32 s33, s33, 0x12000
	s_waitcnt vmcnt(7)
	v_cndmask_b32_e32 v139, 0, v139, vcc
	v_cndmask_b32_e32 v138, 0, v138, vcc
	v_cndmask_b32_e32 v137, 0, v137, vcc
	v_cndmask_b32_e32 v136, 0, v136, vcc
	v_add3_u32 v254, s33, v172, v169
	ds_write_b128 v254, v[136:139]
	s_waitcnt vmcnt(6)
	v_cndmask_b32_e64 v127, 0, v127, s[0:1]
	v_cndmask_b32_e64 v126, 0, v126, s[0:1]
	v_cndmask_b32_e64 v125, 0, v125, s[0:1]
	v_cndmask_b32_e64 v124, 0, v124, s[0:1]
	v_add3_u32 v136, s33, v173, v169
	ds_write_b128 v136, v[124:127]
	s_waitcnt vmcnt(5)
	v_cndmask_b32_e64 v115, 0, v115, s[2:3]
	v_cndmask_b32_e64 v114, 0, v114, s[2:3]
	v_cndmask_b32_e64 v113, 0, v113, s[2:3]
	v_cndmask_b32_e64 v112, 0, v112, s[2:3]
	v_add3_u32 v124, s33, v174, v169
	ds_write_b128 v124, v[112:115]
	s_waitcnt vmcnt(4)
	v_cndmask_b32_e64 v112, 0, v116, s[4:5]
	v_add3_u32 v116, s33, v175, v169
	s_min_u32 s33, s30, 13
	s_lshl_b32 s33, s33, 7
	v_cndmask_b32_e64 v115, 0, v119, s[4:5]
	v_cndmask_b32_e64 v114, 0, v118, s[4:5]
	v_cndmask_b32_e64 v113, 0, v117, s[4:5]
	s_add_u32 s34, s12, s33
	ds_write_b128 v116, v[112:115]
	s_waitcnt vmcnt(3)
	ds_write_b128 v254, v[120:123] offset:36864
	s_waitcnt vmcnt(2)
	ds_write_b128 v136, v[128:131] offset:36864
	s_waitcnt vmcnt(1)
	ds_write_b128 v124, v[132:135] offset:36864
	s_waitcnt vmcnt(0)
	ds_write_b128 v116, v[140:143] offset:36864
	s_addc_u32 s35, s13, 0
	global_load_dwordx4 v[136:139], v176, s[34:35] offset:256
	global_load_dwordx4 v[124:127], v177, s[34:35] offset:256
	global_load_dwordx4 v[112:115], v178, s[34:35] offset:256
	global_load_dwordx4 v[116:119], v179, s[34:35] offset:256
	s_add_u32 s34, s14, s33
	s_addc_u32 s35, s15, 0
	v_lshl_add_u64 v[120:121], v[160:161], 1, s[34:35]
	v_lshl_add_u64 v[128:129], v[162:163], 1, s[34:35]
	v_lshl_add_u64 v[132:133], v[164:165], 1, s[34:35]
	v_lshl_add_u64 v[140:141], v[166:167], 1, s[34:35]
	global_load_dwordx4 v[120:123], v[120:121], off offset:256
	s_nop 0
	global_load_dwordx4 v[128:131], v[128:129], off offset:256
	s_nop 0
	global_load_dwordx4 v[132:135], v[132:133], off offset:256
	s_nop 0
	global_load_dwordx4 v[140:143], v[140:141], off offset:256
	v_readfirstlane_b32 s99, v220
	s_nop 3
	s_bitcmp1_b32 s99, 8
	s_cbranch_scc1 .Lgm6r_bar
	s_and_b32 s98, s30, 1
	s_mul_i32 s98, s98, 0x12000
	v_add3_u32 v181, s98, v170, v180
	v_add3_u32 v202, s98, v171, v180
	ds_read_b128 v[198:201], v181
	ds_read_b128 v[242:245], v181 offset:2304
	ds_read_b128 v[246:249], v181 offset:4608
	ds_read_b128 v[182:185], v202 offset:36864
	ds_read_b128 v[186:189], v202 offset:39168
	ds_read_b128 v[190:193], v202 offset:41472
	ds_read_b128 v[194:197], v202 offset:43776
	s_waitcnt lgkmcnt(0)
	v_mfma_f32_16x16x32_bf16 v[156:159], v[182:185], v[198:201], v[156:159]
	v_mfma_f32_16x16x32_bf16 v[152:155], v[186:189], v[198:201], v[152:155]
	v_mfma_f32_16x16x32_bf16 v[148:151], v[190:193], v[198:201], v[148:151]
	v_mfma_f32_16x16x32_bf16 v[144:147], v[194:197], v[198:201], v[144:147]
	v_mfma_f32_16x16x32_bf16 v[108:111], v[182:185], v[242:245], v[108:111]
	v_mfma_f32_16x16x32_bf16 v[104:107], v[186:189], v[242:245], v[104:107]
	v_mfma_f32_16x16x32_bf16 v[100:103], v[190:193], v[242:245], v[100:103]
	v_mfma_f32_16x16x32_bf16 v[96:99], v[194:197], v[242:245], v[96:99]
	v_mfma_f32_16x16x32_bf16 v[92:95], v[182:185], v[246:249], v[92:95]
	v_mfma_f32_16x16x32_bf16 v[88:91], v[186:189], v[246:249], v[88:91]
	v_mfma_f32_16x16x32_bf16 v[84:87], v[190:193], v[246:249], v[84:87]
	v_mfma_f32_16x16x32_bf16 v[80:83], v[194:197], v[246:249], v[80:83]
	ds_read_b128 v[198:201], v181 offset:64
	ds_read_b128 v[242:245], v181 offset:2368
	ds_read_b128 v[246:249], v181 offset:4672
	ds_read_b128 v[182:185], v202 offset:36928
	ds_read_b128 v[186:189], v202 offset:39232
	ds_read_b128 v[190:193], v202 offset:41536
	ds_read_b128 v[194:197], v202 offset:43840
	s_waitcnt lgkmcnt(0)
	v_mfma_f32_16x16x32_bf16 v[156:159], v[182:185], v[198:201], v[156:159]
	v_mfma_f32_16x16x32_bf16 v[152:155], v[186:189], v[198:201], v[152:155]
	v_mfma_f32_16x16x32_bf16 v[148:151], v[190:193], v[198:201], v[148:151]
	v_mfma_f32_16x16x32_bf16 v[144:147], v[194:197], v[198:201], v[144:147]
	v_mfma_f32_16x16x32_bf16 v[108:111], v[182:185], v[242:245], v[108:111]
	v_mfma_f32_16x16x32_bf16 v[104:107], v[186:189], v[242:245], v[104:107]
	v_mfma_f32_16x16x32_bf16 v[100:103], v[190:193], v[242:245], v[100:103]
	v_mfma_f32_16x16x32_bf16 v[96:99], v[194:197], v[242:245], v[96:99]
	v_mfma_f32_16x16x32_bf16 v[92:95], v[182:185], v[246:249], v[92:95]
	v_mfma_f32_16x16x32_bf16 v[88:91], v[186:189], v[246:249], v[88:91]
	v_mfma_f32_16x16x32_bf16 v[84:87], v[190:193], v[246:249], v[84:87]
	v_mfma_f32_16x16x32_bf16 v[80:83], v[194:197], v[246:249], v[80:83]
; template <int MI, int NJ, bool SWAP, class AP, class BP>
; DI void gemm_main(f32x4 (&acc)[MI][NJ], const AP& ap, int a_kstep, const BP& bp, int b_kstep, int nk, bf16_t* smem) {
;     ...
;     __syncthreads();
;   }
; DI void ffnup_tile(const Params& p, int layer, int b, int mt, int tn, bf16_t* smem) {
;     ...
;   {
;     bf16_t* dstb = (wn < 2 ? U : V) + (wn & 1) * 64 + quad * 4;
; #pragma unroll
;     for (int i = 0; i < 8; ++i) {
;       const int row = wm * 128 + i * 16 + l15, s = s0 + row;
;       const float rs = (s >= 0 && s < S_) ? rstd_from16((const float*)(p.ws + O_SSQ) + ((size_t)b * S_ + s) * 16, 1.f / 1024.f) : 0.f;
.Lgm6r_bar:
	s_waitcnt lgkmcnt(0)
	s_barrier
	s_add_i32 s30, s30, 1
	s_cmp_lg_u32 s30, 16
	s_cbranch_scc1 .Lgm6r_main
	s_nop 7
	s_nop 7
.Lgm6_done:
	s_waitcnt vmcnt(5)
	v_mov_b32_e32 v115, v220
	s_movk_i32 s0, 0xff80
	v_and_b32_e32 v113, 15, v115
	v_ashrrev_i32_e32 v112, 1, v115
	s_waitcnt vmcnt(4)
	v_and_or_b32 v118, v112, s0, v113
	v_add_u32_e32 v116, s29, v118
	s_lshl_b64 s[2:3], s[10:11], 12
	v_cmp_gt_u32_e32 vcc, s22, v116
	v_mov_b32_e32 v112, 0
	v_mov_b32_e32 v114, 0
	s_and_saveexec_b64 s[0:1], vcc
	s_cbranch_execz .LBB0_1052
	s_waitcnt vmcnt(3)
	v_or_b32_e32 v120, s2, v116
	v_mov_b32_e32 v121, s3
	v_lshlrev_b64 v[120:121], 6, v[120:121]
	s_waitcnt vmcnt(1)
	v_lshl_add_u64 v[132:133], s[8:9], 0, v[120:121]
	v_bfe_u32 v244, v132, 6, 8
	v_lshlrev_b32_e32 v244, 3, v244
	v_add_u32_e32 v244, 0x24010, v244
	v_or_b32_e32 v246, 2, v132
	ds_read_b64 v[248:249], v244
	s_waitcnt lgkmcnt(0)
	v_cmp_ne_u32_e64 s[100:101], v248, v246
	s_nop 1
	s_and_saveexec_b64 s[98:99], s[100:101]
	s_cbranch_execz .LrcG0_0
	global_load_dwordx4 v[120:123], v[132:133], off
	global_load_dwordx4 v[124:127], v[132:133], off offset:16
	global_load_dwordx4 v[128:131], v[132:133], off offset:32
	s_nop 0
	global_load_dwordx4 v[132:135], v[132:133], off offset:48
	s_waitcnt vmcnt(3)
	v_mov_b32_e32 v136, v121
	v_mov_b32_e32 v137, v122
	v_mov_b32_e32 v121, v123
	s_waitcnt vmcnt(2)
	v_mov_b32_e32 v122, v125
	v_mov_b32_e32 v123, v126
	v_mov_b32_e32 v125, v127
	v_pk_add_f32 v[120:121], v[136:137], v[120:121]
	v_pk_add_f32 v[122:123], v[122:123], v[124:125]
	v_pk_add_f32 v[120:121], v[120:121], v[120:121] op_sel:[0,1] op_sel_hi:[1,0]
	v_pk_add_f32 v[122:123], v[122:123], v[122:123] op_sel:[0,1] op_sel_hi:[1,0]
	s_waitcnt vmcnt(1)
	v_add_f32_e32 v126, v128, v129
	v_add_f32_e32 v128, v130, v131
	s_waitcnt vmcnt(0)
	v_mov_b32_e32 v127, v134
	v_mov_b32_e32 v129, v135
	v_mov_b32_e32 v121, v132
	v_mov_b32_e32 v123, v133
	v_pk_add_f32 v[124:125], v[126:127], v[128:129]
	v_pk_add_f32 v[120:121], v[120:121], v[122:123]
	s_nop 0
	v_pk_add_f32 v[120:121], v[120:121], v[124:125]
	s_nop 0
	v_add_f32_e32 v114, v120, v121
	v_fmamk_f32 v114, v114, 0x3a800000, v168
	v_mul_f32_e32 v117, 0x4b800000, v114
	v_cmp_gt_f32_e32 vcc, s24, v114
	s_nop 1
	s_nop 0
	v_cndmask_b32_e32 v114, v114, v117, vcc
	v_rsq_f32_e32 v114, v114
	s_nop 0
	v_mul_f32_e32 v117, 0x45800000, v114
	v_cndmask_b32_e32 v114, v114, v117, vcc
	s_nop 0
	v_mov_b32_e32 v247, v114
	ds_write_b64 v244, v[246:247]

; template <int MI, int NJ, bool SWAP, class AP, class BP>
; DI void gemm_main(f32x4 (&acc)[MI][NJ], const AP& ap, int a_kstep, const BP& bp, int b_kstep, int nk, bf16_t* smem) {
;     ...
;   for (int kt = 0; kt < nk; ++kt) {
;     const int buf = kt & 1;
;     sstore(buf ^ 1);
;     gload(kt + 2 < nk ? kt + 2 : nk - 1);
;     __builtin_amdgcn_sched_barrier(0);
;     const bf16_t* As = smem + buf * L::STAGE + (wm * 16 * MI + l15) * LDT + quad * 8;
;     const bf16_t* Bs = smem + buf * L::STAGE + L::A_ELEMS + (wn * 16 * NJ + l15) * LDT + quad * 8;
; #pragma unroll
;     for (int ks = 0; ks < 2; ++ks) {
;       if (MI * NJ >= 32 && ks == 1) asm volatile("" ::: "memory");
;       bf16x8 b[NJ];
; #pragma unroll
;       for (int j = 0; j < NJ; ++j) b[j] = *(const bf16x8*)(Bs + j * 16 * LDT + ks * 32);
.LBB0_2083:
	s_cmp_eq_u32 s42, 0xfde
	s_cbranch_scc1 .Lgm14r_main
	s_and_b32 s98, s43, 1
	s_mul_i32 s98, s98, 0x12000
	v_add3_u32 v206, s98, v171, v180
	v_add3_u32 v181, s98, v170, v180
	ds_read_b128 v[198:201], v181
	ds_read_b128 v[202:205], v181 offset:2304
	ds_read_b128 v[182:185], v206 offset:36864
	ds_read_b128 v[186:189], v206 offset:39168
	ds_read_b128 v[190:193], v206 offset:41472
	ds_read_b128 v[194:197], v206 offset:43776

; DI f32x4 mfma16(bf16x8 a, bf16x8 b, f32x4 c) { return __builtin_amdgcn_mfma_f32_16x16x32_bf16(a, b, c, 0, 0, 0); }
; template <int MI, int NJ, bool SWAP, class AP, class BP>
; DI void gemm_main(f32x4 (&acc)[MI][NJ], const AP& ap, int a_kstep, const BP& bp, int b_kstep, int nk, bf16_t* smem) {
;     ...
;   auto gload = [&](int kt) {
;     const bf16_t* ab = ap.base + (size_t)kt * a_kstep; const bf16_t* bb = bp.base + (size_t)kt * b_kstep;
; #pragma unroll
;     for (int i = 0; i < CA; ++i) ra[i] = *(const u32x4*)(ab + pa[i]);
; #pragma unroll
;     for (int i = 0; i < CB; ++i) rb[i] = *(const u32x4*)(bb + pb[i]);
;   };
;   auto sstore = [&](int buf) {
;     bf16_t* As = smem + buf * L::STAGE; bf16_t* Bs = As + L::A_ELEMS;
; #pragma unroll
;     for (int i = 0; i < CA; ++i) { const int c = tid + NTHR * i; *(u32x4*)(As + (c >> 3) * LDT + (c & 7) * 8) = oka[i] ? ra[i] : (u32x4){0u, 0u, 0u, 0u}; }
; #pragma unroll
;     for (int i = 0; i < CB; ++i) { const int c = tid + NTHR * i; *(u32x4*)(Bs + (c >> 3) * LDT + (c & 7) * 8) = rb[i]; }
;   };
;   gload(0); sstore(0); gload(nk > 1 ? 1 : 0); __syncthreads();
; #pragma unroll 1
;   for (int kt = 0; kt < nk; ++kt) {
;     const int buf = kt & 1;
;     sstore(buf ^ 1);
;     gload(kt + 2 < nk ? kt + 2 : nk - 1);
;     __builtin_amdgcn_sched_barrier(0);
;     const bf16_t* As = smem + buf * L::STAGE + (wm * 16 * MI + l15) * LDT + quad * 8;
;     const bf16_t* Bs = smem + buf * L::STAGE + L::A_ELEMS + (wn * 16 * NJ + l15) * LDT + quad * 8;
; #pragma unroll
;     for (int ks = 0; ks < 2; ++ks) {
;       if (MI * NJ >= 32 && ks == 1) asm volatile("" ::: "memory");
;       bf16x8 b[NJ];
; #pragma unroll
;       for (int j = 0; j < NJ; ++j) b[j] = *(const bf16x8*)(Bs + j * 16 * LDT + ks * 32);
; #pragma unroll
;       for (int i = 0; i < MI; ++i) {
;         const bf16x8 a = *(const bf16x8*)(As + i * 16 * LDT + ks * 32);
; #pragma unroll
;         for (int j = 0; j < NJ; ++j) acc[i][j] = SWAP ? mfma16(b[j], a, acc[i][j]) : mfma16(a, b[j], acc[i][j]);
;       }
.Lgm14_exit:
	v_mfma_f32_16x16x32_bf16 v[28:31], v[182:185], v[242:245], v[28:31]
	v_mfma_f32_16x16x32_bf16 v[8:11], v[182:185], v[246:249], v[8:11]
	v_mfma_f32_16x16x32_bf16 v[24:27], v[186:189], v[242:245], v[24:27]
	v_mfma_f32_16x16x32_bf16 v[4:7], v[186:189], v[246:249], v[4:7]
	v_mfma_f32_16x16x32_bf16 v[20:23], v[190:193], v[242:245], v[20:23]
	v_mfma_f32_16x16x32_bf16 v[0:3], v[190:193], v[246:249], v[0:3]
	v_mfma_f32_16x16x32_bf16 v[12:15], v[194:197], v[242:245], v[12:15]
	v_mfma_f32_16x16x32_bf16 v[16:19], v[194:197], v[246:249], v[16:19]
	s_nop 7
	s_branch .Lgm14_done
.Lgm14r_main:
	s_and_b32 s46, s43, 1
	s_min_u32 s44, s43, 13
	s_xor_b32 s45, s46, 1
	s_lshl_b32 s47, s44, 7
	s_mul_i32 s45, s45, 0x12000
	s_waitcnt vmcnt(7)
	v_cndmask_b32_e32 v143, 0, v143, vcc
	v_cndmask_b32_e32 v142, 0, v142, vcc
	v_cndmask_b32_e32 v141, 0, v141, vcc
	v_cndmask_b32_e32 v140, 0, v140, vcc
	s_add_u32 s44, s18, s47
	v_add3_u32 v250, s45, v172, v169
	s_waitcnt vmcnt(6)
	v_cndmask_b32_e64 v131, 0, v131, s[0:1]
	v_cndmask_b32_e64 v130, 0, v130, s[0:1]
	v_cndmask_b32_e64 v129, 0, v129, s[0:1]
	v_cndmask_b32_e64 v128, 0, v128, s[0:1]
	s_waitcnt vmcnt(5)
	v_cndmask_b32_e64 v115, 0, v115, s[2:3]
	v_cndmask_b32_e64 v114, 0, v114, s[2:3]
	v_cndmask_b32_e64 v113, 0, v113, s[2:3]
	v_cndmask_b32_e64 v112, 0, v112, s[2:3]
	s_waitcnt vmcnt(4)
	v_cndmask_b32_e64 v135, 0, v135, s[4:5]
	v_cndmask_b32_e64 v134, 0, v134, s[4:5]
	v_cndmask_b32_e64 v133, 0, v133, s[4:5]
	v_cndmask_b32_e64 v132, 0, v132, s[4:5]
	v_add3_u32 v251, s45, v173, v169
	v_add3_u32 v252, s45, v174, v169
	v_add3_u32 v253, s45, v175, v169
	s_addc_u32 s45, s19, 0
	ds_write_b128 v250, v[140:143]
	ds_write_b128 v251, v[128:131]
	ds_write_b128 v252, v[112:115]
	ds_write_b128 v253, v[132:135]
	s_waitcnt vmcnt(3)
	ds_write_b128 v250, v[116:119] offset:36864
	s_waitcnt vmcnt(2)
	ds_write_b128 v251, v[120:123] offset:36864
	s_waitcnt vmcnt(1)
	ds_write_b128 v252, v[124:127] offset:36864
	s_waitcnt vmcnt(0)
	ds_write_b128 v253, v[136:139] offset:36864
	global_load_dwordx4 v[140:143], v176, s[44:45] offset:256
	global_load_dwordx4 v[128:131], v177, s[44:45] offset:256
	global_load_dwordx4 v[112:115], v178, s[44:45] offset:256
	global_load_dwordx4 v[132:135], v179, s[44:45] offset:256
	s_add_u32 s44, s20, s47
	s_addc_u32 s45, s21, 0
	v_lshl_add_u64 v[116:117], v[160:161], 1, s[44:45]
	v_lshl_add_u64 v[120:121], v[162:163], 1, s[44:45]
	v_lshl_add_u64 v[124:125], v[164:165], 1, s[44:45]
	v_lshl_add_u64 v[136:137], v[166:167], 1, s[44:45]
	global_load_dwordx4 v[116:119], v[116:117], off offset:256
	s_nop 0
	global_load_dwordx4 v[120:123], v[120:121], off offset:256
	s_nop 0
	global_load_dwordx4 v[124:127], v[124:125], off offset:256
	s_nop 0
	global_load_dwordx4 v[136:139], v[136:137], off offset:256
	v_readfirstlane_b32 s99, v220
	s_nop 3
	s_bitcmp1_b32 s99, 8
	s_cbranch_scc1 .Lgm14r_bar
	s_and_b32 s98, s43, 1
	s_mul_i32 s98, s98, 0x12000
	v_add3_u32 v206, s98, v171, v180
	v_add3_u32 v181, s98, v170, v180
	ds_read_b128 v[198:201], v181
	ds_read_b128 v[202:205], v181 offset:2304
	ds_read_b128 v[242:245], v181 offset:4608
	ds_read_b128 v[182:185], v206 offset:36864
	ds_read_b128 v[186:189], v206 offset:39168
	ds_read_b128 v[190:193], v206 offset:41472
	ds_read_b128 v[194:197], v206 offset:43776
	s_waitcnt lgkmcnt(0)
	v_mfma_f32_16x16x32_bf16 v[156:159], v[182:185], v[198:201], v[156:159]
	v_mfma_f32_16x16x32_bf16 v[152:155], v[186:189], v[198:201], v[152:155]
	v_mfma_f32_16x16x32_bf16 v[148:151], v[190:193], v[198:201], v[148:151]
	v_mfma_f32_16x16x32_bf16 v[144:147], v[194:197], v[198:201], v[144:147]
	v_mfma_f32_16x16x32_bf16 v[108:111], v[182:185], v[202:205], v[108:111]
	v_mfma_f32_16x16x32_bf16 v[104:107], v[186:189], v[202:205], v[104:107]
	v_mfma_f32_16x16x32_bf16 v[100:103], v[190:193], v[202:205], v[100:103]
	v_mfma_f32_16x16x32_bf16 v[96:99], v[194:197], v[202:205], v[96:99]
	v_mfma_f32_16x16x32_bf16 v[92:95], v[182:185], v[242:245], v[92:95]
	v_mfma_f32_16x16x32_bf16 v[88:91], v[186:189], v[242:245], v[88:91]
	v_mfma_f32_16x16x32_bf16 v[84:87], v[190:193], v[242:245], v[84:87]
	v_mfma_f32_16x16x32_bf16 v[80:83], v[194:197], v[242:245], v[80:83]
	ds_read_b128 v[198:201], v181 offset:64
	ds_read_b128 v[202:205], v181 offset:2368
	ds_read_b128 v[242:245], v181 offset:4672
	ds_read_b128 v[182:185], v206 offset:36928
	ds_read_b128 v[186:189], v206 offset:39232
	ds_read_b128 v[190:193], v206 offset:41536
	ds_read_b128 v[194:197], v206 offset:43840
	s_waitcnt lgkmcnt(0)
	v_mfma_f32_16x16x32_bf16 v[156:159], v[182:185], v[198:201], v[156:159]
	v_mfma_f32_16x16x32_bf16 v[152:155], v[186:189], v[198:201], v[152:155]
	v_mfma_f32_16x16x32_bf16 v[148:151], v[190:193], v[198:201], v[148:151]
	v_mfma_f32_16x16x32_bf16 v[144:147], v[194:197], v[198:201], v[144:147]
	v_mfma_f32_16x16x32_bf16 v[108:111], v[182:185], v[202:205], v[108:111]
	v_mfma_f32_16x16x32_bf16 v[104:107], v[186:189], v[202:205], v[104:107]
	v_mfma_f32_16x16x32_bf16 v[100:103], v[190:193], v[202:205], v[100:103]
	v_mfma_f32_16x16x32_bf16 v[96:99], v[194:197], v[202:205], v[96:99]
	v_mfma_f32_16x16x32_bf16 v[92:95], v[182:185], v[242:245], v[92:95]
	v_mfma_f32_16x16x32_bf16 v[88:91], v[186:189], v[242:245], v[88:91]
	v_mfma_f32_16x16x32_bf16 v[84:87], v[190:193], v[242:245], v[84:87]
	v_mfma_f32_16x16x32_bf16 v[80:83], v[194:197], v[242:245], v[80:83]
; DI int TIDX() { int t = (int)threadIdx.x; asm volatile("" : "+v"(t)); return t; }
; DI f32x4 mfma16(bf16x8 a, bf16x8 b, f32x4 c) { return __builtin_amdgcn_mfma_f32_16x16x32_bf16(a, b, c, 0, 0, 0); }
; template <int MI, int NJ, bool SWAP, class AP, class BP>
; DI void gemm_main(f32x4 (&acc)[MI][NJ], const AP& ap, int a_kstep, const BP& bp, int b_kstep, int nk, bf16_t* smem) {
;     ...
;   for (int kt = 0; kt < nk; ++kt) {
;     const int buf = kt & 1;
;     sstore(buf ^ 1);
;     gload(kt + 2 < nk ? kt + 2 : nk - 1);
;     __builtin_amdgcn_sched_barrier(0);
;     const bf16_t* As = smem + buf * L::STAGE + (wm * 16 * MI + l15) * LDT + quad * 8;
;     const bf16_t* Bs = smem + buf * L::STAGE + L::A_ELEMS + (wn * 16 * NJ + l15) * LDT + quad * 8;
; #pragma unroll
;     for (int ks = 0; ks < 2; ++ks) {
;       if (MI * NJ >= 32 && ks == 1) asm volatile("" ::: "memory");
;       bf16x8 b[NJ];
; #pragma unroll
;       for (int j = 0; j < NJ; ++j) b[j] = *(const bf16x8*)(Bs + j * 16 * LDT + ks * 32);
; #pragma unroll
;       for (int i = 0; i < MI; ++i) {
;         const bf16x8 a = *(const bf16x8*)(As + i * 16 * LDT + ks * 32);
; #pragma unroll
;         for (int j = 0; j < NJ; ++j) acc[i][j] = SWAP ? mfma16(b[j], a, acc[i][j]) : mfma16(a, b[j], acc[i][j]);
;       }
;     }
;     __syncthreads();
;   }
; DI void ffnup_tile(const Params& p, int layer, int b, int mt, int tn, bf16_t* smem) {
;     ...
;   const int tid = TIDX(), lane = tid & 63, wid = tid >> 6, wm = wid >> 2, wn = wid & 3, l15 = lane & 15, quad = lane >> 4;
;   constexpr int LDU = 136; bf16_t* U = smem; bf16_t* V = smem + 256 * LDU;
;   {
;     bf16_t* dstb = (wn < 2 ? U : V) + (wn & 1) * 64 + quad * 4;
; #pragma unroll
;     for (int i = 0; i < 8; ++i) {
;       const int row = wm * 128 + i * 16 + l15, s = s0 + row;
;       const float rs = (s >= 0 && s < S_) ? rstd_from16((const float*)(p.ws + O_SSQ) + ((size_t)b * S_ + s) * 16, 1.f / 1024.f) : 0.f;
.Lgm14r_bar:
	s_waitcnt lgkmcnt(0)
	s_barrier
	s_add_i32 s43, s43, 1
	s_cmp_lg_u32 s43, 16
	s_cbranch_scc1 .Lgm14r_main
	s_nop 7
	s_nop 7
.Lgm14_done:
	s_waitcnt vmcnt(5)
	v_mov_b32_e32 v115, v220
	s_lshl_b64 s[2:3], s[16:17], 12
	v_and_b32_e32 v113, 15, v115
	v_ashrrev_i32_e32 v112, 1, v115
	s_waitcnt vmcnt(3)
	v_and_or_b32 v118, v112, s33, v113
	v_add_u32_e32 v117, s42, v118
	v_cmp_gt_u32_e32 vcc, s28, v117
	v_mov_b32_e32 v112, 0
	v_mov_b32_e32 v114, 0
	s_and_saveexec_b64 s[0:1], vcc
	s_cbranch_execz .LBB0_2086
	s_waitcnt vmcnt(2)
	v_or_b32_e32 v120, s2, v117
	v_mov_b32_e32 v121, s3
	v_lshlrev_b64 v[120:121], 6, v[120:121]
	v_lshl_add_u64 v[132:133], s[6:7], 0, v[120:121]
	v_bfe_u32 v244, v132, 6, 8
	v_lshlrev_b32_e32 v244, 3, v244
	v_add_u32_e32 v244, 0x24010, v244
	v_or_b32_e32 v246, 4, v132
	ds_read_b64 v[248:249], v244
	s_waitcnt lgkmcnt(0)
	v_cmp_ne_u32_e64 s[100:101], v248, v246
	s_nop 1
	s_and_saveexec_b64 s[98:99], s[100:101]
	s_cbranch_execz .LrcG1_0
	global_load_dwordx4 v[120:123], v[132:133], off
	global_load_dwordx4 v[124:127], v[132:133], off offset:16
	global_load_dwordx4 v[128:131], v[132:133], off offset:32
	s_nop 0
	global_load_dwordx4 v[132:135], v[132:133], off offset:48
	s_waitcnt vmcnt(3)
	v_mov_b32_e32 v136, v121
	v_mov_b32_e32 v137, v122
	v_mov_b32_e32 v121, v123
	s_waitcnt vmcnt(2)
	v_mov_b32_e32 v122, v125
	v_mov_b32_e32 v123, v126
	v_mov_b32_e32 v125, v127
	v_pk_add_f32 v[120:121], v[136:137], v[120:121]
	v_pk_add_f32 v[122:123], v[122:123], v[124:125]
	v_pk_add_f32 v[120:121], v[120:121], v[120:121] op_sel:[0,1] op_sel_hi:[1,0]
	v_pk_add_f32 v[122:123], v[122:123], v[122:123] op_sel:[0,1] op_sel_hi:[1,0]
	s_waitcnt vmcnt(1)
	v_add_f32_e32 v126, v128, v129
	v_add_f32_e32 v128, v130, v131
	s_waitcnt vmcnt(0)
	v_mov_b32_e32 v127, v134
	v_mov_b32_e32 v129, v135
	v_mov_b32_e32 v121, v132
	v_mov_b32_e32 v123, v133
	v_pk_add_f32 v[124:125], v[126:127], v[128:129]
	v_pk_add_f32 v[120:121], v[120:121], v[122:123]
	s_nop 0
	v_pk_add_f32 v[120:121], v[120:121], v[124:125]
	s_nop 0
	v_add_f32_e32 v114, v120, v121
	v_fmamk_f32 v114, v114, 0x3a800000, v168
	v_mul_f32_e32 v116, 0x4b800000, v114
	v_cmp_gt_f32_e32 vcc, s34, v114
	s_nop 1
	s_nop 0
	v_cndmask_b32_e32 v114, v114, v116, vcc
	v_rsq_f32_e32 v114, v114
	s_nop 0
	v_mul_f32_e32 v116, 0x45800000, v114
	v_cndmask_b32_e32 v114, v114, v116, vcc
	s_nop 0
	v_mov_b32_e32 v247, v114
	ds_write_b64 v244, v[246:247]
